# pass1: raw rows prefetched two chunks ahead (second register buffer, parity-selected top block); on top of pass2 T layout
# baseline (speedup 1.0000x reference)
.LBB0_1150:
	s_ashr_i32 s0, s2, 6
	v_mov_b32_e32 v180, 0
	v_mov_b32_e32 v181, 0
	v_mov_b32_e32 v182, 0
	v_mov_b32_e32 v183, 0
	v_mov_b32_e32 v184, 0
	v_mov_b32_e32 v185, 0
	v_mov_b32_e32 v186, 0
	v_mov_b32_e32 v187, 0
	s_ashr_i32 s1, s0, 31
	s_lshl_b32 s3, s2, 8
	s_lshl_b64 s[0:1], s[0:1], 12
	s_and_b32 s3, s3, 0xf00
	s_or_b32 s4, s0, s3
	s_mov_b32 s5, s1
	v_lshl_add_u64 v[8:9], s[4:5], 0, v[54:55]
	v_mov_b64_e32 v[10:11], s[52:53]
	s_movk_i32 s6, 0x1600
	v_mad_u64_u32 v[10:11], s[4:5], v8, s6, v[10:11]
	s_lshl_b32 s3, s2, 4
	v_mad_i32_i24 v11, v9, s6, v11
	s_and_b32 s54, s3, 0x300
	v_lshl_add_u64 v[8:9], v[10:11], 0, s[54:55]
	v_mov_b32_e32 v61, v16
	v_lshl_add_u64 v[8:9], v[8:9], 0, v[60:61]
	global_load_dwordx4 v[42:45], v[8:9], off offset:2560
	global_load_dwordx4 v[46:49], v[8:9], off offset:3584
	s_lshl_b32 s4, s8, 1
	s_and_b32 s4, s4, 0x300
	v_mov_b32_e32 v8, s4
	v_readfirstlane_b32 s4, v17
	s_ashr_i32 s5, s4, 6
	s_lshl_b32 s4, s5, 4
	v_or_b32_e32 v10, s4, v64
	s_and_b32 s3, s9, 0xf00
	v_lshlrev_b32_e32 v12, 1, v10
	v_or_b32_e32 v10, s4, v56
	v_lshlrev_b32_e32 v74, 1, v10
	v_or_b32_e32 v10, s4, v67
	s_or_b32 s0, s0, s3
	v_mov_b32_e32 v9, v16
	v_lshlrev_b32_e32 v13, 1, v10
	v_lshl_add_u64 v[10:11], s[0:1], 0, v[54:55]
	v_mad_u64_u32 v[8:9], s[0:1], v10, s6, v[8:9]
	v_mad_i32_i24 v9, v11, s6, v9
	v_mov_b32_e32 v61, 0
	v_add_u32_e32 v76, 0, v74
	v_lshl_add_u64 v[62:63], v[58:59], 0, v[8:9]
	s_mov_b64 s[6:7], 0
	v_add_u32_e32 v78, v65, v12
	v_add_u32_e32 v73, v66, v13
	v_mov_b32_e32 v8, 0
	v_mov_b32_e32 v9, v61
	v_mov_b32_e32 v10, v61
	v_mov_b32_e32 v11, v61
	v_mov_b32_e32 v12, 0
	v_mov_b32_e32 v13, v61
	v_mov_b32_e32 v14, v61
	v_mov_b32_e32 v15, v61
	v_mov_b32_e32 v18, 0
	v_mov_b32_e32 v19, v61
	v_mov_b32_e32 v20, v61
	v_mov_b32_e32 v21, v61
	v_mov_b32_e32 v22, 0
	v_mov_b32_e32 v23, v61
	v_mov_b32_e32 v24, v61
	v_mov_b32_e32 v25, v61
	v_mov_b32_e32 v26, 0
	v_mov_b32_e32 v27, v61
	v_mov_b32_e32 v28, v61
	v_mov_b32_e32 v29, v61
	v_mov_b32_e32 v30, 0
	v_mov_b32_e32 v31, v61
	v_mov_b32_e32 v32, v61
	v_mov_b32_e32 v33, v61
	v_mov_b32_e32 v34, 0
	v_mov_b32_e32 v35, v61
	v_mov_b32_e32 v36, v61
	v_mov_b32_e32 v37, v61
	v_mov_b32_e32 v38, 0
	v_mov_b32_e32 v39, v61
	v_mov_b32_e32 v40, v61
	v_mov_b32_e32 v41, v61
	v_add_u32_e32 v77, v76, v69
	s_mov_b32 s0, 0x6b2c000
	v_add_co_u32_e64 v216, s[0:1], s0, v62
	s_nop 1
	v_addc_co_u32_e64 v217, s[0:1], 0, v63, s[0:1]
	global_load_dwordx4 v[208:211], v[216:217], off offset:2560
	global_load_dwordx4 v[212:215], v[216:217], off offset:3584
	s_branch .LBB0_1152

.LBB0_1152:
	s_bitcmp1_b32 s6, 14
	s_cbranch_scc1 .Lp1_odd
	s_waitcnt vmcnt(3)
	ds_write_b128 v70, v[42:45] offset:17408
	s_waitcnt vmcnt(2)
	ds_write_b128 v70, v[46:49] offset:37888
	s_cmp_ge_u32 s6, 0x108000
	s_cbranch_scc1 .Lp1_top
	v_lshl_add_u64 v[42:43], v[62:63], 0, s[6:7]
	s_mov_b32 s0, 0x6b58000
	v_add_co_u32_e64 v46, s[0:1], s0, v42
	s_nop 1
	v_addc_co_u32_e64 v47, s[0:1], 0, v43, s[0:1]
	global_load_dwordx4 v[42:45], v[46:47], off offset:2560
	s_nop 0
	global_load_dwordx4 v[46:49], v[46:47], off offset:3584
	s_branch .Lp1_top
.Lp1_odd:
	s_waitcnt vmcnt(3)
	ds_write_b128 v70, v[208:211] offset:17408
	s_waitcnt vmcnt(2)
	ds_write_b128 v70, v[212:215] offset:37888
	s_cmp_ge_u32 s6, 0x108000
	s_cbranch_scc1 .Lp1_top
	v_lshl_add_u64 v[208:209], v[62:63], 0, s[6:7]
	s_mov_b32 s0, 0x6b58000
	v_add_co_u32_e64 v212, s[0:1], s0, v208
	s_nop 1
	v_addc_co_u32_e64 v213, s[0:1], 0, v209, s[0:1]
	global_load_dwordx4 v[208:211], v[212:213], off offset:2560
	s_nop 0
	global_load_dwordx4 v[212:215], v[212:213], off offset:3584
.Lp1_top:
	v_and_or_b32 v50, v221, 64, v56
	s_waitcnt lgkmcnt(0)
	s_barrier
	ds_read_b64_tr_b16 v[80:81], v78 offset:17408
	ds_read_b64_tr_b16 v[82:83], v78 offset:18688
	ds_read_u16_d16_hi v180, v77 offset:17408
	ds_read_u16_d16_hi v181, v77 offset:17728
	ds_read_u16_d16_hi v182, v77 offset:18048
	ds_read_u16_d16_hi v183, v77 offset:18368
	ds_read_u16_d16_hi v184, v77 offset:22528
	ds_read_u16_d16_hi v185, v77 offset:22848
	ds_read_u16_d16_hi v186, v77 offset:23168
	ds_read_u16_d16_hi v187, v77 offset:23488
	s_waitcnt lgkmcnt(8)
	v_mfma_f32_16x16x32_bf16 v[84:87], v[0:3], v[80:83], 0
	v_lshlrev_b32_e32 v79, 2, v50
	v_mfma_f32_16x16x32_bf16 v[80:83], v[4:7], v[80:83], 0
	s_nop 5
	ds_bpermute_b32 v50, v79, v87 offset:192
	s_waitcnt lgkmcnt(0)
	v_exp_f32_e32 v188, v180
	v_exp_f32_e32 v189, v181
	v_exp_f32_e32 v190, v182
	v_exp_f32_e32 v191, v183
	v_exp_f32_e32 v192, v184
	v_exp_f32_e32 v193, v185
	v_exp_f32_e32 v194, v186
	v_exp_f32_e32 v195, v187
	v_sub_f32_e32 v196, v50, v80
	v_sub_f32_e32 v197, v50, v81
	v_sub_f32_e32 v198, v50, v82
	v_sub_f32_e32 v199, v50, v83
	v_sub_f32_e32 v200, v50, v84
	v_sub_f32_e32 v201, v50, v85
	v_sub_f32_e32 v202, v50, v86
	v_sub_f32_e32 v203, v50, v87
	v_exp_f32_e32 v196, v196
	v_exp_f32_e32 v197, v197
	v_exp_f32_e32 v198, v198
	v_exp_f32_e32 v199, v199
	v_exp_f32_e32 v200, v200
	v_exp_f32_e32 v201, v201
	v_exp_f32_e32 v202, v202
	v_exp_f32_e32 v203, v203
	v_sub_f32_e32 v188, 1.0, v188
	v_sub_f32_e32 v189, 1.0, v189
	v_sub_f32_e32 v190, 1.0, v190
	v_sub_f32_e32 v191, 1.0, v191
	v_sub_f32_e32 v192, 1.0, v192
	v_sub_f32_e32 v193, 1.0, v193
	v_sub_f32_e32 v194, 1.0, v194
	v_sub_f32_e32 v195, 1.0, v195
	v_mul_f32_e32 v196, v196, v188
	v_mul_f32_e32 v197, v197, v189
	v_mul_f32_e32 v198, v198, v190
	v_mul_f32_e32 v199, v199, v191
	v_mul_f32_e32 v200, v200, v192
	v_mul_f32_e32 v201, v201, v193
	v_mul_f32_e32 v202, v202, v194
	v_mul_f32_e32 v203, v203, v195
	v_cvt_pk_bf16_f32 v204, v196, v197
	v_cvt_pk_bf16_f32 v205, v198, v199
	v_cvt_pk_bf16_f32 v206, v200, v201
	v_cvt_pk_bf16_f32 v207, v202, v203
	ds_write_b16 v77, v204 offset:27648
	ds_write_b16_d16_hi v77, v204 offset:27968
	ds_write_b16 v77, v205 offset:28288
	ds_write_b16_d16_hi v77, v205 offset:28608
	ds_write_b16 v77, v206 offset:32768
	ds_write_b16_d16_hi v77, v206 offset:33088
	ds_write_b16 v77, v207 offset:33408
	ds_write_b16_d16_hi v77, v207 offset:33728
	s_and_saveexec_b64 s[0:1], vcc
	s_cbranch_execz .LBB0_1151
	v_exp_f32_e32 v51, v50
	v_add_u32_e32 v52, v76, v74
	ds_write_b32 v52, v51 offset:56832
	s_branch .LBB0_1151
.LBB0_1154:
	s_waitcnt vmcnt(1)
	ds_write_b128 v70, v[208:211] offset:17408
	s_waitcnt vmcnt(0)
	ds_write_b128 v70, v[212:215] offset:37888
	s_waitcnt lgkmcnt(0)
	s_barrier
	ds_read_b64_tr_b16 v[42:43], v78 offset:17408
	ds_read_b64_tr_b16 v[44:45], v78 offset:18688
	ds_read_u16_d16_hi v180, v77 offset:17408
	ds_read_u16_d16_hi v181, v77 offset:17728
	ds_read_u16_d16_hi v182, v77 offset:18048
	ds_read_u16_d16_hi v183, v77 offset:18368
	ds_read_u16_d16_hi v184, v77 offset:22528
	ds_read_u16_d16_hi v185, v77 offset:22848
	ds_read_u16_d16_hi v186, v77 offset:23168
	ds_read_u16_d16_hi v187, v77 offset:23488
	s_waitcnt lgkmcnt(8)
	v_mfma_f32_16x16x32_bf16 v[48:51], v[0:3], v[42:45], 0
	v_or_b32_e32 v46, 0xc0, v79
	v_mfma_f32_16x16x32_bf16 v[42:45], v[4:7], v[42:45], 0
	s_nop 5
	ds_bpermute_b32 v46, v46, v51
	s_waitcnt lgkmcnt(0)
	v_exp_f32_e32 v188, v180
	v_exp_f32_e32 v189, v181
	v_exp_f32_e32 v190, v182
	v_exp_f32_e32 v191, v183
	v_exp_f32_e32 v192, v184
	v_exp_f32_e32 v193, v185
	v_exp_f32_e32 v194, v186
	v_exp_f32_e32 v195, v187
	v_sub_f32_e32 v196, v46, v42
	v_sub_f32_e32 v197, v46, v43
	v_sub_f32_e32 v198, v46, v44
	v_sub_f32_e32 v199, v46, v45
	v_sub_f32_e32 v200, v46, v48
	v_sub_f32_e32 v201, v46, v49
	v_sub_f32_e32 v202, v46, v50
	v_sub_f32_e32 v203, v46, v51
	v_exp_f32_e32 v196, v196
	v_exp_f32_e32 v197, v197
	v_exp_f32_e32 v198, v198
	v_exp_f32_e32 v199, v199
	v_exp_f32_e32 v200, v200
	v_exp_f32_e32 v201, v201
	v_exp_f32_e32 v202, v202
	v_exp_f32_e32 v203, v203
	v_sub_f32_e32 v188, 1.0, v188
	v_sub_f32_e32 v189, 1.0, v189
	v_sub_f32_e32 v190, 1.0, v190
	v_sub_f32_e32 v191, 1.0, v191
	v_sub_f32_e32 v192, 1.0, v192
	v_sub_f32_e32 v193, 1.0, v193
	v_sub_f32_e32 v194, 1.0, v194
	v_sub_f32_e32 v195, 1.0, v195
	v_mul_f32_e32 v196, v196, v188
	v_mul_f32_e32 v197, v197, v189
	v_mul_f32_e32 v198, v198, v190
	v_mul_f32_e32 v199, v199, v191
	v_mul_f32_e32 v200, v200, v192
	v_mul_f32_e32 v201, v201, v193
	v_mul_f32_e32 v202, v202, v194
	v_mul_f32_e32 v203, v203, v195
	v_cvt_pk_bf16_f32 v204, v196, v197
	v_cvt_pk_bf16_f32 v205, v198, v199
	v_cvt_pk_bf16_f32 v206, v200, v201
	v_cvt_pk_bf16_f32 v207, v202, v203
	ds_write_b16 v77, v204 offset:27648
	ds_write_b16_d16_hi v77, v204 offset:27968
	ds_write_b16 v77, v205 offset:28288
	ds_write_b16_d16_hi v77, v205 offset:28608
	ds_write_b16 v77, v206 offset:32768
	ds_write_b16_d16_hi v77, v206 offset:33088
	ds_write_b16 v77, v207 offset:33408
	ds_write_b16_d16_hi v77, v207 offset:33728
	s_and_saveexec_b64 s[0:1], vcc
	s_cbranch_execz .LBB0_1156
	v_exp_f32_e32 v42, v46
	v_add_u32_e32 v43, v76, v74
	ds_write_b32 v43, v42 offset:56832
